# same as the nt-store version; code after the FFN-up epilogue shifted by 96 bytes (placement of the FFN-down loop)
# baseline (speedup 1.0000x reference)
.Lffn_nz:
	s_waitcnt vmcnt(0)
	ds_bpermute_b32 v200, v252, v158
	ds_bpermute_b32 v201, v252, v159
	ds_bpermute_b32 v202, v252, v154
	ds_bpermute_b32 v203, v252, v155
	s_waitcnt lgkmcnt(0)
	ds_bpermute_b32 v204, v252, v62
	ds_bpermute_b32 v205, v252, v63
	ds_bpermute_b32 v206, v252, v58
	ds_bpermute_b32 v207, v252, v59
	v_pk_fma_f32 v[230:231], v[156:157], v[112:113], v[116:117] op_sel_hi:[1,0,0]
	v_pk_fma_f32 v[232:233], v[158:159], v[112:113], v[116:117] op_sel_hi:[1,0,0]
	v_fmac_f32_e32 v230, v201, v113
	v_fmac_f32_e32 v231, v156, v113
	v_fmac_f32_e32 v232, v157, v113
	v_fmac_f32_e32 v233, v158, v113
	v_pk_fma_f32 v[230:231], v[200:201], v[114:115], v[230:231] op_sel_hi:[1,0,1]
	v_pk_fma_f32 v[232:233], v[156:157], v[114:115], v[232:233] op_sel_hi:[1,0,1]
	v_pk_fma_f32 v[234:235], v[152:153], v[118:119], v[122:123] op_sel_hi:[1,0,0]
	v_pk_fma_f32 v[236:237], v[154:155], v[118:119], v[122:123] op_sel_hi:[1,0,0]
	v_fmac_f32_e32 v234, v203, v119
	v_fmac_f32_e32 v235, v152, v119
	v_fmac_f32_e32 v236, v153, v119
	v_fmac_f32_e32 v237, v154, v119
	v_pk_fma_f32 v[234:235], v[202:203], v[120:121], v[234:235] op_sel_hi:[1,0,1]
	v_pk_fma_f32 v[236:237], v[152:153], v[120:121], v[236:237] op_sel_hi:[1,0,1]
	v_pk_mul_f32 v[238:239], v[230:231], v[230:231]
	v_pk_mul_f32 v[240:241], v[232:233], v[232:233]
	v_pk_fma_f32 v[238:239], v[238:239], v[248:249], v[246:247]
	v_pk_fma_f32 v[240:241], v[240:241], v[248:249], v[246:247]
	v_pk_mul_f32 v[238:239], v[230:231], v[238:239]
	v_pk_mul_f32 v[240:241], v[232:233], v[240:241]
	v_exp_f32_e32 v238, v238
	v_exp_f32_e32 v239, v239
	v_exp_f32_e32 v240, v240
	v_exp_f32_e32 v241, v241
	v_pk_add_f32 v[238:239], v[238:239], 1.0 op_sel_hi:[1,0]
	v_pk_add_f32 v[240:241], v[240:241], 1.0 op_sel_hi:[1,0]
	v_rcp_f32_e32 v238, v238
	v_rcp_f32_e32 v239, v239
	v_rcp_f32_e32 v240, v240
	v_rcp_f32_e32 v241, v241
	v_pk_mul_f32 v[230:231], v[230:231], v[234:235]
	v_pk_mul_f32 v[232:233], v[232:233], v[236:237]
	v_pk_mul_f32 v[238:239], v[230:231], v[238:239]
	v_pk_mul_f32 v[240:241], v[232:233], v[240:241]
	v_cvt_pk_bf16_f32 v212, v238, v239
	v_cvt_pk_bf16_f32 v213, v240, v241
	s_mov_b64 vcc, s[30:31]
	s_nop 0
	v_mov_b32_dpp v214, v212 quad_perm:[1,0,3,2] row_mask:0xf bank_mask:0xf
	v_mov_b32_dpp v215, v213 quad_perm:[1,0,3,2] row_mask:0xf bank_mask:0xf
	v_perm_b32 v216, v214, v212, v253
	v_perm_b32 v217, v215, v213, v253
	s_nop 1
	v_mov_b32_dpp v218, v216 quad_perm:[2,3,0,1] row_mask:0xf bank_mask:0xf
	v_mov_b32_dpp v219, v217 quad_perm:[2,3,0,1] row_mask:0xf bank_mask:0xf
	v_cndmask_b32_e32 v176, v216, v219, vcc
	v_cndmask_b32_e32 v177, v218, v217, vcc
	s_waitcnt lgkmcnt(0)
	s_mov_b64 vcc, s[28:29]
	v_cndmask_b32_e32 v208, v150, v158, vcc
	v_cndmask_b32_e32 v209, v151, v159, vcc
	v_cndmask_b32_e32 v210, v146, v154, vcc
	v_cndmask_b32_e32 v211, v147, v155, vcc
	ds_bpermute_b32 v200, v252, v208
	ds_bpermute_b32 v201, v252, v209
	ds_bpermute_b32 v202, v252, v210
	ds_bpermute_b32 v203, v252, v211
	v_pk_fma_f32 v[230:231], v[60:61], v[124:125], v[128:129] op_sel_hi:[1,0,0]
	v_pk_fma_f32 v[232:233], v[62:63], v[124:125], v[128:129] op_sel_hi:[1,0,0]
	v_fmac_f32_e32 v230, v205, v125
	v_fmac_f32_e32 v231, v60, v125
	v_fmac_f32_e32 v232, v61, v125
	v_fmac_f32_e32 v233, v62, v125
	v_pk_fma_f32 v[230:231], v[204:205], v[126:127], v[230:231] op_sel_hi:[1,0,1]
	v_pk_fma_f32 v[232:233], v[60:61], v[126:127], v[232:233] op_sel_hi:[1,0,1]
	v_pk_fma_f32 v[234:235], v[56:57], v[130:131], v[134:135] op_sel_hi:[1,0,0]
	v_pk_fma_f32 v[236:237], v[58:59], v[130:131], v[134:135] op_sel_hi:[1,0,0]
	v_fmac_f32_e32 v234, v207, v131
	v_fmac_f32_e32 v235, v56, v131
	v_fmac_f32_e32 v236, v57, v131
	v_fmac_f32_e32 v237, v58, v131
	v_pk_fma_f32 v[234:235], v[206:207], v[132:133], v[234:235] op_sel_hi:[1,0,1]
	v_pk_fma_f32 v[236:237], v[56:57], v[132:133], v[236:237] op_sel_hi:[1,0,1]
	v_pk_mul_f32 v[238:239], v[230:231], v[230:231]
	v_pk_mul_f32 v[240:241], v[232:233], v[232:233]
	v_pk_fma_f32 v[238:239], v[238:239], v[248:249], v[246:247]
	v_pk_fma_f32 v[240:241], v[240:241], v[248:249], v[246:247]
	v_pk_mul_f32 v[238:239], v[230:231], v[238:239]
	v_pk_mul_f32 v[240:241], v[232:233], v[240:241]
	v_exp_f32_e32 v238, v238
	v_exp_f32_e32 v239, v239
	v_exp_f32_e32 v240, v240
	v_exp_f32_e32 v241, v241
	v_pk_add_f32 v[238:239], v[238:239], 1.0 op_sel_hi:[1,0]
	v_pk_add_f32 v[240:241], v[240:241], 1.0 op_sel_hi:[1,0]
	v_rcp_f32_e32 v238, v238
	v_rcp_f32_e32 v239, v239
	v_rcp_f32_e32 v240, v240
	v_rcp_f32_e32 v241, v241
	v_pk_mul_f32 v[230:231], v[230:231], v[234:235]
	v_pk_mul_f32 v[232:233], v[232:233], v[236:237]
	v_pk_mul_f32 v[238:239], v[230:231], v[238:239]
	v_pk_mul_f32 v[240:241], v[232:233], v[240:241]
	v_cvt_pk_bf16_f32 v212, v238, v239
	v_cvt_pk_bf16_f32 v213, v240, v241
	s_mov_b64 vcc, s[30:31]
	s_nop 0
	v_mov_b32_dpp v214, v212 quad_perm:[1,0,3,2] row_mask:0xf bank_mask:0xf
	v_mov_b32_dpp v215, v213 quad_perm:[1,0,3,2] row_mask:0xf bank_mask:0xf
	v_perm_b32 v216, v214, v212, v253
	v_perm_b32 v217, v215, v213, v253
	s_nop 1
	v_mov_b32_dpp v218, v216 quad_perm:[2,3,0,1] row_mask:0xf bank_mask:0xf
	v_mov_b32_dpp v219, v217 quad_perm:[2,3,0,1] row_mask:0xf bank_mask:0xf
	v_cndmask_b32_e32 v178, v216, v219, vcc
	v_cndmask_b32_e32 v179, v218, v217, vcc
	s_movk_i32 s15, 0x1002
	v_cmp_gt_i32_e64 s[24:25], s15, v251
	s_sub_u32 s84, s58, 0x2c00
	s_subb_u32 s85, s59, 0
	s_and_b64 s[24:25], s[24:25], s[36:37]
	s_mov_b64 exec, s[24:25]
	global_store_dwordx4 v250, v[176:179], s[84:85] nt
	s_mov_b64 exec, -1
	s_nop 0
	s_waitcnt lgkmcnt(0)
	s_mov_b64 vcc, s[28:29]
	v_cndmask_b32_e32 v208, v54, v62, vcc
	v_cndmask_b32_e32 v209, v55, v63, vcc
	v_cndmask_b32_e32 v210, v50, v58, vcc
	v_cndmask_b32_e32 v211, v51, v59, vcc
	ds_bpermute_b32 v204, v252, v208
	ds_bpermute_b32 v205, v252, v209
	ds_bpermute_b32 v206, v252, v210
	ds_bpermute_b32 v207, v252, v211
	v_pk_fma_f32 v[230:231], v[148:149], v[112:113], v[116:117] op_sel_hi:[1,0,0]
	v_pk_fma_f32 v[232:233], v[150:151], v[112:113], v[116:117] op_sel_hi:[1,0,0]
	v_fmac_f32_e32 v230, v201, v113
	v_fmac_f32_e32 v231, v148, v113
	v_fmac_f32_e32 v232, v149, v113
	v_fmac_f32_e32 v233, v150, v113
	v_pk_fma_f32 v[230:231], v[200:201], v[114:115], v[230:231] op_sel_hi:[1,0,1]
	v_pk_fma_f32 v[232:233], v[148:149], v[114:115], v[232:233] op_sel_hi:[1,0,1]
	v_pk_fma_f32 v[234:235], v[144:145], v[118:119], v[122:123] op_sel_hi:[1,0,0]
	v_pk_fma_f32 v[236:237], v[146:147], v[118:119], v[122:123] op_sel_hi:[1,0,0]
	v_fmac_f32_e32 v234, v203, v119
	v_fmac_f32_e32 v235, v144, v119
	v_fmac_f32_e32 v236, v145, v119
	v_fmac_f32_e32 v237, v146, v119
	v_pk_fma_f32 v[234:235], v[202:203], v[120:121], v[234:235] op_sel_hi:[1,0,1]
	v_pk_fma_f32 v[236:237], v[144:145], v[120:121], v[236:237] op_sel_hi:[1,0,1]
	v_pk_mul_f32 v[238:239], v[230:231], v[230:231]
	v_pk_mul_f32 v[240:241], v[232:233], v[232:233]
	v_pk_fma_f32 v[238:239], v[238:239], v[248:249], v[246:247]
	v_pk_fma_f32 v[240:241], v[240:241], v[248:249], v[246:247]
	v_pk_mul_f32 v[238:239], v[230:231], v[238:239]
	v_pk_mul_f32 v[240:241], v[232:233], v[240:241]
	v_exp_f32_e32 v238, v238
	v_exp_f32_e32 v239, v239
	v_exp_f32_e32 v240, v240
	v_exp_f32_e32 v241, v241
	v_pk_add_f32 v[238:239], v[238:239], 1.0 op_sel_hi:[1,0]
	v_pk_add_f32 v[240:241], v[240:241], 1.0 op_sel_hi:[1,0]
	v_rcp_f32_e32 v238, v238
	v_rcp_f32_e32 v239, v239
	v_rcp_f32_e32 v240, v240
	v_rcp_f32_e32 v241, v241
	v_pk_mul_f32 v[230:231], v[230:231], v[234:235]
	v_pk_mul_f32 v[232:233], v[232:233], v[236:237]
	v_pk_mul_f32 v[238:239], v[230:231], v[238:239]
	v_pk_mul_f32 v[240:241], v[232:233], v[240:241]
	v_cvt_pk_bf16_f32 v212, v238, v239
	v_cvt_pk_bf16_f32 v213, v240, v241
	s_mov_b64 vcc, s[30:31]
	s_nop 0
	v_mov_b32_dpp v214, v212 quad_perm:[1,0,3,2] row_mask:0xf bank_mask:0xf
	v_mov_b32_dpp v215, v213 quad_perm:[1,0,3,2] row_mask:0xf bank_mask:0xf
	v_perm_b32 v216, v214, v212, v253
	v_perm_b32 v217, v215, v213, v253
	s_nop 1
	v_mov_b32_dpp v218, v216 quad_perm:[2,3,0,1] row_mask:0xf bank_mask:0xf
	v_mov_b32_dpp v219, v217 quad_perm:[2,3,0,1] row_mask:0xf bank_mask:0xf
	v_cndmask_b32_e32 v180, v216, v219, vcc
	v_cndmask_b32_e32 v181, v218, v217, vcc
	s_waitcnt lgkmcnt(0)
	s_mov_b64 vcc, s[28:29]
	v_cndmask_b32_e32 v208, v142, v150, vcc
	v_cndmask_b32_e32 v209, v143, v151, vcc
	v_cndmask_b32_e32 v210, v138, v146, vcc
	v_cndmask_b32_e32 v211, v139, v147, vcc
	ds_bpermute_b32 v200, v252, v208
	ds_bpermute_b32 v201, v252, v209
	ds_bpermute_b32 v202, v252, v210
	ds_bpermute_b32 v203, v252, v211
	v_pk_fma_f32 v[230:231], v[52:53], v[124:125], v[128:129] op_sel_hi:[1,0,0]
	v_pk_fma_f32 v[232:233], v[54:55], v[124:125], v[128:129] op_sel_hi:[1,0,0]
	v_fmac_f32_e32 v230, v205, v125
	v_fmac_f32_e32 v231, v52, v125
	v_fmac_f32_e32 v232, v53, v125
	v_fmac_f32_e32 v233, v54, v125
	v_pk_fma_f32 v[230:231], v[204:205], v[126:127], v[230:231] op_sel_hi:[1,0,1]
	v_pk_fma_f32 v[232:233], v[52:53], v[126:127], v[232:233] op_sel_hi:[1,0,1]
	v_pk_fma_f32 v[234:235], v[48:49], v[130:131], v[134:135] op_sel_hi:[1,0,0]
	v_pk_fma_f32 v[236:237], v[50:51], v[130:131], v[134:135] op_sel_hi:[1,0,0]
	v_fmac_f32_e32 v234, v207, v131
	v_fmac_f32_e32 v235, v48, v131
	v_fmac_f32_e32 v236, v49, v131
	v_fmac_f32_e32 v237, v50, v131
	v_pk_fma_f32 v[234:235], v[206:207], v[132:133], v[234:235] op_sel_hi:[1,0,1]
	v_pk_fma_f32 v[236:237], v[48:49], v[132:133], v[236:237] op_sel_hi:[1,0,1]
	v_pk_mul_f32 v[238:239], v[230:231], v[230:231]
	v_pk_mul_f32 v[240:241], v[232:233], v[232:233]
	v_pk_fma_f32 v[238:239], v[238:239], v[248:249], v[246:247]
	v_pk_fma_f32 v[240:241], v[240:241], v[248:249], v[246:247]
	v_pk_mul_f32 v[238:239], v[230:231], v[238:239]
	v_pk_mul_f32 v[240:241], v[232:233], v[240:241]
	v_exp_f32_e32 v238, v238
	v_exp_f32_e32 v239, v239
	v_exp_f32_e32 v240, v240
	v_exp_f32_e32 v241, v241
	v_pk_add_f32 v[238:239], v[238:239], 1.0 op_sel_hi:[1,0]
	v_pk_add_f32 v[240:241], v[240:241], 1.0 op_sel_hi:[1,0]
	v_rcp_f32_e32 v238, v238
	v_rcp_f32_e32 v239, v239
	v_rcp_f32_e32 v240, v240
	v_rcp_f32_e32 v241, v241
	v_pk_mul_f32 v[230:231], v[230:231], v[234:235]
	v_pk_mul_f32 v[232:233], v[232:233], v[236:237]
	v_pk_mul_f32 v[238:239], v[230:231], v[238:239]
	v_pk_mul_f32 v[240:241], v[232:233], v[240:241]
	v_cvt_pk_bf16_f32 v212, v238, v239
	v_cvt_pk_bf16_f32 v213, v240, v241
	s_mov_b64 vcc, s[30:31]
	s_nop 0
	v_mov_b32_dpp v214, v212 quad_perm:[1,0,3,2] row_mask:0xf bank_mask:0xf
	v_mov_b32_dpp v215, v213 quad_perm:[1,0,3,2] row_mask:0xf bank_mask:0xf
	v_perm_b32 v216, v214, v212, v253
	v_perm_b32 v217, v215, v213, v253
	s_nop 1
	v_mov_b32_dpp v218, v216 quad_perm:[2,3,0,1] row_mask:0xf bank_mask:0xf
	v_mov_b32_dpp v219, v217 quad_perm:[2,3,0,1] row_mask:0xf bank_mask:0xf
	v_cndmask_b32_e32 v182, v216, v219, vcc
	v_cndmask_b32_e32 v183, v218, v217, vcc
	s_movk_i32 s15, 0xff2
	v_cmp_gt_i32_e64 s[24:25], s15, v251
	s_add_u32 s84, s58, 0x13400
	s_addc_u32 s85, s59, 0
	s_mov_b64 exec, s[24:25]
	global_store_dwordx4 v250, v[180:183], s[84:85] nt
	s_mov_b64 exec, -1
	s_nop 0
	s_waitcnt lgkmcnt(0)
	s_mov_b64 vcc, s[28:29]
	v_cndmask_b32_e32 v208, v46, v54, vcc
	v_cndmask_b32_e32 v209, v47, v55, vcc
	v_cndmask_b32_e32 v210, v42, v50, vcc
	v_cndmask_b32_e32 v211, v43, v51, vcc
	ds_bpermute_b32 v204, v252, v208
	ds_bpermute_b32 v205, v252, v209
	ds_bpermute_b32 v206, v252, v210
	ds_bpermute_b32 v207, v252, v211
	v_pk_fma_f32 v[230:231], v[140:141], v[112:113], v[116:117] op_sel_hi:[1,0,0]
	v_pk_fma_f32 v[232:233], v[142:143], v[112:113], v[116:117] op_sel_hi:[1,0,0]
	v_fmac_f32_e32 v230, v201, v113
	v_fmac_f32_e32 v231, v140, v113
	v_fmac_f32_e32 v232, v141, v113
	v_fmac_f32_e32 v233, v142, v113
	v_pk_fma_f32 v[230:231], v[200:201], v[114:115], v[230:231] op_sel_hi:[1,0,1]
	v_pk_fma_f32 v[232:233], v[140:141], v[114:115], v[232:233] op_sel_hi:[1,0,1]
	v_pk_fma_f32 v[234:235], v[136:137], v[118:119], v[122:123] op_sel_hi:[1,0,0]
	v_pk_fma_f32 v[236:237], v[138:139], v[118:119], v[122:123] op_sel_hi:[1,0,0]
	v_fmac_f32_e32 v234, v203, v119
	v_fmac_f32_e32 v235, v136, v119
	v_fmac_f32_e32 v236, v137, v119
	v_fmac_f32_e32 v237, v138, v119
	v_pk_fma_f32 v[234:235], v[202:203], v[120:121], v[234:235] op_sel_hi:[1,0,1]
	v_pk_fma_f32 v[236:237], v[136:137], v[120:121], v[236:237] op_sel_hi:[1,0,1]
	v_pk_mul_f32 v[238:239], v[230:231], v[230:231]
	v_pk_mul_f32 v[240:241], v[232:233], v[232:233]
	v_pk_fma_f32 v[238:239], v[238:239], v[248:249], v[246:247]
	v_pk_fma_f32 v[240:241], v[240:241], v[248:249], v[246:247]
	v_pk_mul_f32 v[238:239], v[230:231], v[238:239]
	v_pk_mul_f32 v[240:241], v[232:233], v[240:241]
	v_exp_f32_e32 v238, v238
	v_exp_f32_e32 v239, v239
	v_exp_f32_e32 v240, v240
	v_exp_f32_e32 v241, v241
	v_pk_add_f32 v[238:239], v[238:239], 1.0 op_sel_hi:[1,0]
	v_pk_add_f32 v[240:241], v[240:241], 1.0 op_sel_hi:[1,0]
	v_rcp_f32_e32 v238, v238
	v_rcp_f32_e32 v239, v239
	v_rcp_f32_e32 v240, v240
	v_rcp_f32_e32 v241, v241
	v_pk_mul_f32 v[230:231], v[230:231], v[234:235]
	v_pk_mul_f32 v[232:233], v[232:233], v[236:237]
	v_pk_mul_f32 v[238:239], v[230:231], v[238:239]
	v_pk_mul_f32 v[240:241], v[232:233], v[240:241]
	v_cvt_pk_bf16_f32 v212, v238, v239
	v_cvt_pk_bf16_f32 v213, v240, v241
	s_mov_b64 vcc, s[30:31]
	s_nop 0
	v_mov_b32_dpp v214, v212 quad_perm:[1,0,3,2] row_mask:0xf bank_mask:0xf
	v_mov_b32_dpp v215, v213 quad_perm:[1,0,3,2] row_mask:0xf bank_mask:0xf
	v_perm_b32 v216, v214, v212, v253
	v_perm_b32 v217, v215, v213, v253
	s_nop 1
	v_mov_b32_dpp v218, v216 quad_perm:[2,3,0,1] row_mask:0xf bank_mask:0xf
	v_mov_b32_dpp v219, v217 quad_perm:[2,3,0,1] row_mask:0xf bank_mask:0xf
	v_cndmask_b32_e32 v176, v216, v219, vcc
	v_cndmask_b32_e32 v177, v218, v217, vcc
	s_waitcnt lgkmcnt(0)
	s_mov_b64 vcc, s[28:29]
	v_cndmask_b32_e32 v208, v110, v142, vcc
	v_cndmask_b32_e32 v209, v111, v143, vcc
	v_cndmask_b32_e32 v210, v98, v138, vcc
	v_cndmask_b32_e32 v211, v99, v139, vcc
	ds_bpermute_b32 v200, v252, v208
	ds_bpermute_b32 v201, v252, v209
	ds_bpermute_b32 v202, v252, v210
	ds_bpermute_b32 v203, v252, v211
	v_pk_fma_f32 v[230:231], v[44:45], v[124:125], v[128:129] op_sel_hi:[1,0,0]
	v_pk_fma_f32 v[232:233], v[46:47], v[124:125], v[128:129] op_sel_hi:[1,0,0]
	v_fmac_f32_e32 v230, v205, v125
	v_fmac_f32_e32 v231, v44, v125
	v_fmac_f32_e32 v232, v45, v125
	v_fmac_f32_e32 v233, v46, v125
	v_pk_fma_f32 v[230:231], v[204:205], v[126:127], v[230:231] op_sel_hi:[1,0,1]
	v_pk_fma_f32 v[232:233], v[44:45], v[126:127], v[232:233] op_sel_hi:[1,0,1]
	v_pk_fma_f32 v[234:235], v[40:41], v[130:131], v[134:135] op_sel_hi:[1,0,0]
	v_pk_fma_f32 v[236:237], v[42:43], v[130:131], v[134:135] op_sel_hi:[1,0,0]
	v_fmac_f32_e32 v234, v207, v131
	v_fmac_f32_e32 v235, v40, v131
	v_fmac_f32_e32 v236, v41, v131
	v_fmac_f32_e32 v237, v42, v131
	v_pk_fma_f32 v[234:235], v[206:207], v[132:133], v[234:235] op_sel_hi:[1,0,1]
	v_pk_fma_f32 v[236:237], v[40:41], v[132:133], v[236:237] op_sel_hi:[1,0,1]
	v_pk_mul_f32 v[238:239], v[230:231], v[230:231]
	v_pk_mul_f32 v[240:241], v[232:233], v[232:233]
	v_pk_fma_f32 v[238:239], v[238:239], v[248:249], v[246:247]
	v_pk_fma_f32 v[240:241], v[240:241], v[248:249], v[246:247]
	v_pk_mul_f32 v[238:239], v[230:231], v[238:239]
	v_pk_mul_f32 v[240:241], v[232:233], v[240:241]
	v_exp_f32_e32 v238, v238
	v_exp_f32_e32 v239, v239
	v_exp_f32_e32 v240, v240
	v_exp_f32_e32 v241, v241
	v_pk_add_f32 v[238:239], v[238:239], 1.0 op_sel_hi:[1,0]
	v_pk_add_f32 v[240:241], v[240:241], 1.0 op_sel_hi:[1,0]
	v_rcp_f32_e32 v238, v238
	v_rcp_f32_e32 v239, v239
	v_rcp_f32_e32 v240, v240
	v_rcp_f32_e32 v241, v241
	v_pk_mul_f32 v[230:231], v[230:231], v[234:235]
	v_pk_mul_f32 v[232:233], v[232:233], v[236:237]
	v_pk_mul_f32 v[238:239], v[230:231], v[238:239]
	v_pk_mul_f32 v[240:241], v[232:233], v[240:241]
	v_cvt_pk_bf16_f32 v212, v238, v239
	v_cvt_pk_bf16_f32 v213, v240, v241
	s_mov_b64 vcc, s[30:31]
	s_nop 0
	v_mov_b32_dpp v214, v212 quad_perm:[1,0,3,2] row_mask:0xf bank_mask:0xf
	v_mov_b32_dpp v215, v213 quad_perm:[1,0,3,2] row_mask:0xf bank_mask:0xf
	v_perm_b32 v216, v214, v212, v253
	v_perm_b32 v217, v215, v213, v253
	s_nop 1
	v_mov_b32_dpp v218, v216 quad_perm:[2,3,0,1] row_mask:0xf bank_mask:0xf
	v_mov_b32_dpp v219, v217 quad_perm:[2,3,0,1] row_mask:0xf bank_mask:0xf
	v_cndmask_b32_e32 v178, v216, v219, vcc
	v_cndmask_b32_e32 v179, v218, v217, vcc
	s_movk_i32 s15, 0xfe2
	v_cmp_gt_i32_e64 s[24:25], s15, v251
	s_add_u32 s84, s58, 0x29400
	s_addc_u32 s85, s59, 0
	s_mov_b64 exec, s[24:25]
	global_store_dwordx4 v250, v[176:179], s[84:85] nt
	s_mov_b64 exec, -1
	s_nop 0
	s_waitcnt lgkmcnt(0)
	s_mov_b64 vcc, s[28:29]
	v_cndmask_b32_e32 v208, v38, v46, vcc
	v_cndmask_b32_e32 v209, v39, v47, vcc
	v_cndmask_b32_e32 v210, v34, v42, vcc
	v_cndmask_b32_e32 v211, v35, v43, vcc
	ds_bpermute_b32 v204, v252, v208
	ds_bpermute_b32 v205, v252, v209
	ds_bpermute_b32 v206, v252, v210
	ds_bpermute_b32 v207, v252, v211
	v_pk_fma_f32 v[230:231], v[108:109], v[112:113], v[116:117] op_sel_hi:[1,0,0]
	v_pk_fma_f32 v[232:233], v[110:111], v[112:113], v[116:117] op_sel_hi:[1,0,0]
	v_fmac_f32_e32 v230, v201, v113
	v_fmac_f32_e32 v231, v108, v113
	v_fmac_f32_e32 v232, v109, v113
	v_fmac_f32_e32 v233, v110, v113
	v_pk_fma_f32 v[230:231], v[200:201], v[114:115], v[230:231] op_sel_hi:[1,0,1]
	v_pk_fma_f32 v[232:233], v[108:109], v[114:115], v[232:233] op_sel_hi:[1,0,1]
	v_pk_fma_f32 v[234:235], v[96:97], v[118:119], v[122:123] op_sel_hi:[1,0,0]
	v_pk_fma_f32 v[236:237], v[98:99], v[118:119], v[122:123] op_sel_hi:[1,0,0]
	v_fmac_f32_e32 v234, v203, v119
	v_fmac_f32_e32 v235, v96, v119
	v_fmac_f32_e32 v236, v97, v119
	v_fmac_f32_e32 v237, v98, v119
	v_pk_fma_f32 v[234:235], v[202:203], v[120:121], v[234:235] op_sel_hi:[1,0,1]
	v_pk_fma_f32 v[236:237], v[96:97], v[120:121], v[236:237] op_sel_hi:[1,0,1]
	v_pk_mul_f32 v[238:239], v[230:231], v[230:231]
	v_pk_mul_f32 v[240:241], v[232:233], v[232:233]
	v_pk_fma_f32 v[238:239], v[238:239], v[248:249], v[246:247]
	v_pk_fma_f32 v[240:241], v[240:241], v[248:249], v[246:247]
	v_pk_mul_f32 v[238:239], v[230:231], v[238:239]
	v_pk_mul_f32 v[240:241], v[232:233], v[240:241]
	v_exp_f32_e32 v238, v238
	v_exp_f32_e32 v239, v239
	v_exp_f32_e32 v240, v240
	v_exp_f32_e32 v241, v241
	v_pk_add_f32 v[238:239], v[238:239], 1.0 op_sel_hi:[1,0]
	v_pk_add_f32 v[240:241], v[240:241], 1.0 op_sel_hi:[1,0]
	v_rcp_f32_e32 v238, v238
	v_rcp_f32_e32 v239, v239
	v_rcp_f32_e32 v240, v240
	v_rcp_f32_e32 v241, v241
	v_pk_mul_f32 v[230:231], v[230:231], v[234:235]
	v_pk_mul_f32 v[232:233], v[232:233], v[236:237]
	v_pk_mul_f32 v[238:239], v[230:231], v[238:239]
	v_pk_mul_f32 v[240:241], v[232:233], v[240:241]
	v_cvt_pk_bf16_f32 v212, v238, v239
	v_cvt_pk_bf16_f32 v213, v240, v241
	s_mov_b64 vcc, s[30:31]
	s_nop 0
	v_mov_b32_dpp v214, v212 quad_perm:[1,0,3,2] row_mask:0xf bank_mask:0xf
	v_mov_b32_dpp v215, v213 quad_perm:[1,0,3,2] row_mask:0xf bank_mask:0xf
	v_perm_b32 v216, v214, v212, v253
	v_perm_b32 v217, v215, v213, v253
	s_nop 1
	v_mov_b32_dpp v218, v216 quad_perm:[2,3,0,1] row_mask:0xf bank_mask:0xf
	v_mov_b32_dpp v219, v217 quad_perm:[2,3,0,1] row_mask:0xf bank_mask:0xf
	v_cndmask_b32_e32 v180, v216, v219, vcc
	v_cndmask_b32_e32 v181, v218, v217, vcc
	s_waitcnt lgkmcnt(0)
	ds_bpermute_b32 v200, v252, v94
	ds_bpermute_b32 v201, v252, v95
	ds_bpermute_b32 v202, v252, v90
	ds_bpermute_b32 v203, v252, v91
	v_pk_fma_f32 v[230:231], v[36:37], v[124:125], v[128:129] op_sel_hi:[1,0,0]
	v_pk_fma_f32 v[232:233], v[38:39], v[124:125], v[128:129] op_sel_hi:[1,0,0]
	v_fmac_f32_e32 v230, v205, v125
	v_fmac_f32_e32 v231, v36, v125
	v_fmac_f32_e32 v232, v37, v125
	v_fmac_f32_e32 v233, v38, v125
	v_pk_fma_f32 v[230:231], v[204:205], v[126:127], v[230:231] op_sel_hi:[1,0,1]
	v_pk_fma_f32 v[232:233], v[36:37], v[126:127], v[232:233] op_sel_hi:[1,0,1]
	v_pk_fma_f32 v[234:235], v[32:33], v[130:131], v[134:135] op_sel_hi:[1,0,0]
	v_pk_fma_f32 v[236:237], v[34:35], v[130:131], v[134:135] op_sel_hi:[1,0,0]
	v_fmac_f32_e32 v234, v207, v131
	v_fmac_f32_e32 v235, v32, v131
	v_fmac_f32_e32 v236, v33, v131
	v_fmac_f32_e32 v237, v34, v131
	v_pk_fma_f32 v[234:235], v[206:207], v[132:133], v[234:235] op_sel_hi:[1,0,1]
	v_pk_fma_f32 v[236:237], v[32:33], v[132:133], v[236:237] op_sel_hi:[1,0,1]
	v_pk_mul_f32 v[238:239], v[230:231], v[230:231]
	v_pk_mul_f32 v[240:241], v[232:233], v[232:233]
	v_pk_fma_f32 v[238:239], v[238:239], v[248:249], v[246:247]
	v_pk_fma_f32 v[240:241], v[240:241], v[248:249], v[246:247]
	v_pk_mul_f32 v[238:239], v[230:231], v[238:239]
	v_pk_mul_f32 v[240:241], v[232:233], v[240:241]
	v_exp_f32_e32 v238, v238
	v_exp_f32_e32 v239, v239
	v_exp_f32_e32 v240, v240
	v_exp_f32_e32 v241, v241
	v_pk_add_f32 v[238:239], v[238:239], 1.0 op_sel_hi:[1,0]
	v_pk_add_f32 v[240:241], v[240:241], 1.0 op_sel_hi:[1,0]
	v_rcp_f32_e32 v238, v238
	v_rcp_f32_e32 v239, v239
	v_rcp_f32_e32 v240, v240
	v_rcp_f32_e32 v241, v241
	v_pk_mul_f32 v[230:231], v[230:231], v[234:235]
	v_pk_mul_f32 v[232:233], v[232:233], v[236:237]
	v_pk_mul_f32 v[238:239], v[230:231], v[238:239]
	v_pk_mul_f32 v[240:241], v[232:233], v[240:241]
	v_cvt_pk_bf16_f32 v212, v238, v239
	v_cvt_pk_bf16_f32 v213, v240, v241
	s_mov_b64 vcc, s[30:31]
	s_nop 0
	v_mov_b32_dpp v214, v212 quad_perm:[1,0,3,2] row_mask:0xf bank_mask:0xf
	v_mov_b32_dpp v215, v213 quad_perm:[1,0,3,2] row_mask:0xf bank_mask:0xf
	v_perm_b32 v216, v214, v212, v253
	v_perm_b32 v217, v215, v213, v253
	s_nop 1
	v_mov_b32_dpp v218, v216 quad_perm:[2,3,0,1] row_mask:0xf bank_mask:0xf
	v_mov_b32_dpp v219, v217 quad_perm:[2,3,0,1] row_mask:0xf bank_mask:0xf
	v_cndmask_b32_e32 v182, v216, v219, vcc
	v_cndmask_b32_e32 v183, v218, v217, vcc
	s_movk_i32 s15, 0xfd2
	v_cmp_gt_i32_e64 s[24:25], s15, v251
	s_add_u32 s84, s58, 0x3f400
	s_addc_u32 s85, s59, 0
	s_mov_b64 exec, s[24:25]
	global_store_dwordx4 v250, v[180:183], s[84:85] nt
	s_mov_b64 exec, -1
	s_nop 0
	s_waitcnt lgkmcnt(0)
	ds_bpermute_b32 v204, v252, v30
	ds_bpermute_b32 v205, v252, v31
	ds_bpermute_b32 v206, v252, v26
	ds_bpermute_b32 v207, v252, v27
	v_pk_fma_f32 v[230:231], v[92:93], v[112:113], v[116:117] op_sel_hi:[1,0,0]
	v_pk_fma_f32 v[232:233], v[94:95], v[112:113], v[116:117] op_sel_hi:[1,0,0]
	v_fmac_f32_e32 v230, v201, v113
	v_fmac_f32_e32 v231, v92, v113
	v_fmac_f32_e32 v232, v93, v113
	v_fmac_f32_e32 v233, v94, v113
	v_pk_fma_f32 v[230:231], v[200:201], v[114:115], v[230:231] op_sel_hi:[1,0,1]
	v_pk_fma_f32 v[232:233], v[92:93], v[114:115], v[232:233] op_sel_hi:[1,0,1]
	v_pk_fma_f32 v[234:235], v[88:89], v[118:119], v[122:123] op_sel_hi:[1,0,0]
	v_pk_fma_f32 v[236:237], v[90:91], v[118:119], v[122:123] op_sel_hi:[1,0,0]
	v_fmac_f32_e32 v234, v203, v119
	v_fmac_f32_e32 v235, v88, v119
	v_fmac_f32_e32 v236, v89, v119
	v_fmac_f32_e32 v237, v90, v119
	v_pk_fma_f32 v[234:235], v[202:203], v[120:121], v[234:235] op_sel_hi:[1,0,1]
	v_pk_fma_f32 v[236:237], v[88:89], v[120:121], v[236:237] op_sel_hi:[1,0,1]
	v_pk_mul_f32 v[238:239], v[230:231], v[230:231]
	v_pk_mul_f32 v[240:241], v[232:233], v[232:233]
	v_pk_fma_f32 v[238:239], v[238:239], v[248:249], v[246:247]
	v_pk_fma_f32 v[240:241], v[240:241], v[248:249], v[246:247]
	v_pk_mul_f32 v[238:239], v[230:231], v[238:239]
	v_pk_mul_f32 v[240:241], v[232:233], v[240:241]
	v_exp_f32_e32 v238, v238
	v_exp_f32_e32 v239, v239
	v_exp_f32_e32 v240, v240
	v_exp_f32_e32 v241, v241
	v_pk_add_f32 v[238:239], v[238:239], 1.0 op_sel_hi:[1,0]
	v_pk_add_f32 v[240:241], v[240:241], 1.0 op_sel_hi:[1,0]
	v_rcp_f32_e32 v238, v238
	v_rcp_f32_e32 v239, v239
	v_rcp_f32_e32 v240, v240
	v_rcp_f32_e32 v241, v241
	v_pk_mul_f32 v[230:231], v[230:231], v[234:235]
	v_pk_mul_f32 v[232:233], v[232:233], v[236:237]
	v_pk_mul_f32 v[238:239], v[230:231], v[238:239]
	v_pk_mul_f32 v[240:241], v[232:233], v[240:241]
	v_cvt_pk_bf16_f32 v212, v238, v239
	v_cvt_pk_bf16_f32 v213, v240, v241
	s_mov_b64 vcc, s[30:31]
	s_nop 0
	v_mov_b32_dpp v214, v212 quad_perm:[1,0,3,2] row_mask:0xf bank_mask:0xf
	v_mov_b32_dpp v215, v213 quad_perm:[1,0,3,2] row_mask:0xf bank_mask:0xf
	v_perm_b32 v216, v214, v212, v253
	v_perm_b32 v217, v215, v213, v253
	s_nop 1
	v_mov_b32_dpp v218, v216 quad_perm:[2,3,0,1] row_mask:0xf bank_mask:0xf
	v_mov_b32_dpp v219, v217 quad_perm:[2,3,0,1] row_mask:0xf bank_mask:0xf
	v_cndmask_b32_e32 v176, v216, v219, vcc
	v_cndmask_b32_e32 v177, v218, v217, vcc
	s_waitcnt lgkmcnt(0)
	s_mov_b64 vcc, s[28:29]
	v_cndmask_b32_e32 v208, v86, v94, vcc
	v_cndmask_b32_e32 v209, v87, v95, vcc
	v_cndmask_b32_e32 v210, v82, v90, vcc
	v_cndmask_b32_e32 v211, v83, v91, vcc
	ds_bpermute_b32 v200, v252, v208
	ds_bpermute_b32 v201, v252, v209
	ds_bpermute_b32 v202, v252, v210
	ds_bpermute_b32 v203, v252, v211
	v_pk_fma_f32 v[230:231], v[28:29], v[124:125], v[128:129] op_sel_hi:[1,0,0]
	v_pk_fma_f32 v[232:233], v[30:31], v[124:125], v[128:129] op_sel_hi:[1,0,0]
	v_fmac_f32_e32 v230, v205, v125
	v_fmac_f32_e32 v231, v28, v125
	v_fmac_f32_e32 v232, v29, v125
	v_fmac_f32_e32 v233, v30, v125
	v_pk_fma_f32 v[230:231], v[204:205], v[126:127], v[230:231] op_sel_hi:[1,0,1]
	v_pk_fma_f32 v[232:233], v[28:29], v[126:127], v[232:233] op_sel_hi:[1,0,1]
	v_pk_fma_f32 v[234:235], v[24:25], v[130:131], v[134:135] op_sel_hi:[1,0,0]
	v_pk_fma_f32 v[236:237], v[26:27], v[130:131], v[134:135] op_sel_hi:[1,0,0]
	v_fmac_f32_e32 v234, v207, v131
	v_fmac_f32_e32 v235, v24, v131
	v_fmac_f32_e32 v236, v25, v131
	v_fmac_f32_e32 v237, v26, v131
	v_pk_fma_f32 v[234:235], v[206:207], v[132:133], v[234:235] op_sel_hi:[1,0,1]
	v_pk_fma_f32 v[236:237], v[24:25], v[132:133], v[236:237] op_sel_hi:[1,0,1]
	v_pk_mul_f32 v[238:239], v[230:231], v[230:231]
	v_pk_mul_f32 v[240:241], v[232:233], v[232:233]
	v_pk_fma_f32 v[238:239], v[238:239], v[248:249], v[246:247]
	v_pk_fma_f32 v[240:241], v[240:241], v[248:249], v[246:247]
	v_pk_mul_f32 v[238:239], v[230:231], v[238:239]
	v_pk_mul_f32 v[240:241], v[232:233], v[240:241]
	v_exp_f32_e32 v238, v238
	v_exp_f32_e32 v239, v239
	v_exp_f32_e32 v240, v240
	v_exp_f32_e32 v241, v241
	v_pk_add_f32 v[238:239], v[238:239], 1.0 op_sel_hi:[1,0]
	v_pk_add_f32 v[240:241], v[240:241], 1.0 op_sel_hi:[1,0]
	v_rcp_f32_e32 v238, v238
	v_rcp_f32_e32 v239, v239
	v_rcp_f32_e32 v240, v240
	v_rcp_f32_e32 v241, v241
	v_pk_mul_f32 v[230:231], v[230:231], v[234:235]
	v_pk_mul_f32 v[232:233], v[232:233], v[236:237]
	v_pk_mul_f32 v[238:239], v[230:231], v[238:239]
	v_pk_mul_f32 v[240:241], v[232:233], v[240:241]
	v_cvt_pk_bf16_f32 v212, v238, v239
	v_cvt_pk_bf16_f32 v213, v240, v241
	s_mov_b64 vcc, s[30:31]
	s_nop 0
	v_mov_b32_dpp v214, v212 quad_perm:[1,0,3,2] row_mask:0xf bank_mask:0xf
	v_mov_b32_dpp v215, v213 quad_perm:[1,0,3,2] row_mask:0xf bank_mask:0xf
	v_perm_b32 v216, v214, v212, v253
	v_perm_b32 v217, v215, v213, v253
	s_nop 1
	v_mov_b32_dpp v218, v216 quad_perm:[2,3,0,1] row_mask:0xf bank_mask:0xf
	v_mov_b32_dpp v219, v217 quad_perm:[2,3,0,1] row_mask:0xf bank_mask:0xf
	v_cndmask_b32_e32 v178, v216, v219, vcc
	v_cndmask_b32_e32 v179, v218, v217, vcc
	s_movk_i32 s15, 0xf86
	v_cmp_gt_i32_e64 s[24:25], s15, v251
	s_add_u32 s84, s58, 0xa7c00
	s_addc_u32 s85, s59, 0
	s_and_b64 s[24:25], s[24:25], s[36:37]
	s_mov_b64 exec, s[24:25]
	global_store_dwordx4 v250, v[176:179], s[84:85] nt
	s_mov_b64 exec, -1
	s_nop 0
	s_waitcnt lgkmcnt(0)
	s_mov_b64 vcc, s[28:29]
	v_cndmask_b32_e32 v208, v22, v30, vcc
	v_cndmask_b32_e32 v209, v23, v31, vcc
	v_cndmask_b32_e32 v210, v18, v26, vcc
	v_cndmask_b32_e32 v211, v19, v27, vcc
	ds_bpermute_b32 v204, v252, v208
	ds_bpermute_b32 v205, v252, v209
	ds_bpermute_b32 v206, v252, v210
	ds_bpermute_b32 v207, v252, v211
	v_pk_fma_f32 v[230:231], v[84:85], v[112:113], v[116:117] op_sel_hi:[1,0,0]
	v_pk_fma_f32 v[232:233], v[86:87], v[112:113], v[116:117] op_sel_hi:[1,0,0]
	v_fmac_f32_e32 v230, v201, v113
	v_fmac_f32_e32 v231, v84, v113
	v_fmac_f32_e32 v232, v85, v113
	v_fmac_f32_e32 v233, v86, v113
	v_pk_fma_f32 v[230:231], v[200:201], v[114:115], v[230:231] op_sel_hi:[1,0,1]
	v_pk_fma_f32 v[232:233], v[84:85], v[114:115], v[232:233] op_sel_hi:[1,0,1]
	v_pk_fma_f32 v[234:235], v[80:81], v[118:119], v[122:123] op_sel_hi:[1,0,0]
	v_pk_fma_f32 v[236:237], v[82:83], v[118:119], v[122:123] op_sel_hi:[1,0,0]
	v_fmac_f32_e32 v234, v203, v119
	v_fmac_f32_e32 v235, v80, v119
	v_fmac_f32_e32 v236, v81, v119
	v_fmac_f32_e32 v237, v82, v119
	v_pk_fma_f32 v[234:235], v[202:203], v[120:121], v[234:235] op_sel_hi:[1,0,1]
	v_pk_fma_f32 v[236:237], v[80:81], v[120:121], v[236:237] op_sel_hi:[1,0,1]
	v_pk_mul_f32 v[238:239], v[230:231], v[230:231]
	v_pk_mul_f32 v[240:241], v[232:233], v[232:233]
	v_pk_fma_f32 v[238:239], v[238:239], v[248:249], v[246:247]
	v_pk_fma_f32 v[240:241], v[240:241], v[248:249], v[246:247]
	v_pk_mul_f32 v[238:239], v[230:231], v[238:239]
	v_pk_mul_f32 v[240:241], v[232:233], v[240:241]
	v_exp_f32_e32 v238, v238
	v_exp_f32_e32 v239, v239
	v_exp_f32_e32 v240, v240
	v_exp_f32_e32 v241, v241
	v_pk_add_f32 v[238:239], v[238:239], 1.0 op_sel_hi:[1,0]
	v_pk_add_f32 v[240:241], v[240:241], 1.0 op_sel_hi:[1,0]
	v_rcp_f32_e32 v238, v238
	v_rcp_f32_e32 v239, v239
	v_rcp_f32_e32 v240, v240
	v_rcp_f32_e32 v241, v241
	v_pk_mul_f32 v[230:231], v[230:231], v[234:235]
	v_pk_mul_f32 v[232:233], v[232:233], v[236:237]
	v_pk_mul_f32 v[238:239], v[230:231], v[238:239]
	v_pk_mul_f32 v[240:241], v[232:233], v[240:241]
	v_cvt_pk_bf16_f32 v212, v238, v239
	v_cvt_pk_bf16_f32 v213, v240, v241
	s_mov_b64 vcc, s[30:31]
	s_nop 0
	v_mov_b32_dpp v214, v212 quad_perm:[1,0,3,2] row_mask:0xf bank_mask:0xf
	v_mov_b32_dpp v215, v213 quad_perm:[1,0,3,2] row_mask:0xf bank_mask:0xf
	v_perm_b32 v216, v214, v212, v253
	v_perm_b32 v217, v215, v213, v253
	s_nop 1
	v_mov_b32_dpp v218, v216 quad_perm:[2,3,0,1] row_mask:0xf bank_mask:0xf
	v_mov_b32_dpp v219, v217 quad_perm:[2,3,0,1] row_mask:0xf bank_mask:0xf
	v_cndmask_b32_e32 v180, v216, v219, vcc
	v_cndmask_b32_e32 v181, v218, v217, vcc
	s_waitcnt lgkmcnt(0)
	s_mov_b64 vcc, s[28:29]
	v_cndmask_b32_e32 v208, v78, v86, vcc
	v_cndmask_b32_e32 v209, v79, v87, vcc
	v_cndmask_b32_e32 v210, v74, v82, vcc
	v_cndmask_b32_e32 v211, v75, v83, vcc
	ds_bpermute_b32 v200, v252, v208
	ds_bpermute_b32 v201, v252, v209
	ds_bpermute_b32 v202, v252, v210
	ds_bpermute_b32 v203, v252, v211
	v_pk_fma_f32 v[230:231], v[20:21], v[124:125], v[128:129] op_sel_hi:[1,0,0]
	v_pk_fma_f32 v[232:233], v[22:23], v[124:125], v[128:129] op_sel_hi:[1,0,0]
	v_fmac_f32_e32 v230, v205, v125
	v_fmac_f32_e32 v231, v20, v125
	v_fmac_f32_e32 v232, v21, v125
	v_fmac_f32_e32 v233, v22, v125
	v_pk_fma_f32 v[230:231], v[204:205], v[126:127], v[230:231] op_sel_hi:[1,0,1]
	v_pk_fma_f32 v[232:233], v[20:21], v[126:127], v[232:233] op_sel_hi:[1,0,1]
	v_pk_fma_f32 v[234:235], v[16:17], v[130:131], v[134:135] op_sel_hi:[1,0,0]
	v_pk_fma_f32 v[236:237], v[18:19], v[130:131], v[134:135] op_sel_hi:[1,0,0]
	v_fmac_f32_e32 v234, v207, v131
	v_fmac_f32_e32 v235, v16, v131
	v_fmac_f32_e32 v236, v17, v131
	v_fmac_f32_e32 v237, v18, v131
	v_pk_fma_f32 v[234:235], v[206:207], v[132:133], v[234:235] op_sel_hi:[1,0,1]
	v_pk_fma_f32 v[236:237], v[16:17], v[132:133], v[236:237] op_sel_hi:[1,0,1]
	v_pk_mul_f32 v[238:239], v[230:231], v[230:231]
	v_pk_mul_f32 v[240:241], v[232:233], v[232:233]
	v_pk_fma_f32 v[238:239], v[238:239], v[248:249], v[246:247]
	v_pk_fma_f32 v[240:241], v[240:241], v[248:249], v[246:247]
	v_pk_mul_f32 v[238:239], v[230:231], v[238:239]
	v_pk_mul_f32 v[240:241], v[232:233], v[240:241]
	v_exp_f32_e32 v238, v238
	v_exp_f32_e32 v239, v239
	v_exp_f32_e32 v240, v240
	v_exp_f32_e32 v241, v241
	v_pk_add_f32 v[238:239], v[238:239], 1.0 op_sel_hi:[1,0]
	v_pk_add_f32 v[240:241], v[240:241], 1.0 op_sel_hi:[1,0]
	v_rcp_f32_e32 v238, v238
	v_rcp_f32_e32 v239, v239
	v_rcp_f32_e32 v240, v240
	v_rcp_f32_e32 v241, v241
	v_pk_mul_f32 v[230:231], v[230:231], v[234:235]
	v_pk_mul_f32 v[232:233], v[232:233], v[236:237]
	v_pk_mul_f32 v[238:239], v[230:231], v[238:239]
	v_pk_mul_f32 v[240:241], v[232:233], v[240:241]
	v_cvt_pk_bf16_f32 v212, v238, v239
	v_cvt_pk_bf16_f32 v213, v240, v241
	s_mov_b64 vcc, s[30:31]
	s_nop 0
	v_mov_b32_dpp v214, v212 quad_perm:[1,0,3,2] row_mask:0xf bank_mask:0xf
	v_mov_b32_dpp v215, v213 quad_perm:[1,0,3,2] row_mask:0xf bank_mask:0xf
	v_perm_b32 v216, v214, v212, v253
	v_perm_b32 v217, v215, v213, v253
	s_nop 1
	v_mov_b32_dpp v218, v216 quad_perm:[2,3,0,1] row_mask:0xf bank_mask:0xf
	v_mov_b32_dpp v219, v217 quad_perm:[2,3,0,1] row_mask:0xf bank_mask:0xf
	v_cndmask_b32_e32 v182, v216, v219, vcc
	v_cndmask_b32_e32 v183, v218, v217, vcc
	s_movk_i32 s15, 0xf76
	v_cmp_gt_i32_e64 s[24:25], s15, v251
	s_add_u32 s84, s58, 0xbdc00
	s_addc_u32 s85, s59, 0
	s_mov_b64 exec, s[24:25]
	global_store_dwordx4 v250, v[180:183], s[84:85] nt
	s_mov_b64 exec, -1
	s_nop 0
	s_waitcnt lgkmcnt(0)
	s_mov_b64 vcc, s[28:29]
	v_cndmask_b32_e32 v208, v14, v22, vcc
	v_cndmask_b32_e32 v209, v15, v23, vcc
	v_cndmask_b32_e32 v210, v10, v18, vcc
	v_cndmask_b32_e32 v211, v11, v19, vcc
	ds_bpermute_b32 v204, v252, v208
	ds_bpermute_b32 v205, v252, v209
	ds_bpermute_b32 v206, v252, v210
	ds_bpermute_b32 v207, v252, v211
	v_pk_fma_f32 v[230:231], v[76:77], v[112:113], v[116:117] op_sel_hi:[1,0,0]
	v_pk_fma_f32 v[232:233], v[78:79], v[112:113], v[116:117] op_sel_hi:[1,0,0]
	v_fmac_f32_e32 v230, v201, v113
	v_fmac_f32_e32 v231, v76, v113
	v_fmac_f32_e32 v232, v77, v113
	v_fmac_f32_e32 v233, v78, v113
	v_pk_fma_f32 v[230:231], v[200:201], v[114:115], v[230:231] op_sel_hi:[1,0,1]
	v_pk_fma_f32 v[232:233], v[76:77], v[114:115], v[232:233] op_sel_hi:[1,0,1]
	v_pk_fma_f32 v[234:235], v[72:73], v[118:119], v[122:123] op_sel_hi:[1,0,0]
	v_pk_fma_f32 v[236:237], v[74:75], v[118:119], v[122:123] op_sel_hi:[1,0,0]
	v_fmac_f32_e32 v234, v203, v119
	v_fmac_f32_e32 v235, v72, v119
	v_fmac_f32_e32 v236, v73, v119
	v_fmac_f32_e32 v237, v74, v119
	v_pk_fma_f32 v[234:235], v[202:203], v[120:121], v[234:235] op_sel_hi:[1,0,1]
	v_pk_fma_f32 v[236:237], v[72:73], v[120:121], v[236:237] op_sel_hi:[1,0,1]
	v_pk_mul_f32 v[238:239], v[230:231], v[230:231]
	v_pk_mul_f32 v[240:241], v[232:233], v[232:233]
	v_pk_fma_f32 v[238:239], v[238:239], v[248:249], v[246:247]
	v_pk_fma_f32 v[240:241], v[240:241], v[248:249], v[246:247]
	v_pk_mul_f32 v[238:239], v[230:231], v[238:239]
	v_pk_mul_f32 v[240:241], v[232:233], v[240:241]
	v_exp_f32_e32 v238, v238
	v_exp_f32_e32 v239, v239
	v_exp_f32_e32 v240, v240
	v_exp_f32_e32 v241, v241
	v_pk_add_f32 v[238:239], v[238:239], 1.0 op_sel_hi:[1,0]
	v_pk_add_f32 v[240:241], v[240:241], 1.0 op_sel_hi:[1,0]
	v_rcp_f32_e32 v238, v238
	v_rcp_f32_e32 v239, v239
	v_rcp_f32_e32 v240, v240
	v_rcp_f32_e32 v241, v241
	v_pk_mul_f32 v[230:231], v[230:231], v[234:235]
	v_pk_mul_f32 v[232:233], v[232:233], v[236:237]
	v_pk_mul_f32 v[238:239], v[230:231], v[238:239]
	v_pk_mul_f32 v[240:241], v[232:233], v[240:241]
	v_cvt_pk_bf16_f32 v212, v238, v239
	v_cvt_pk_bf16_f32 v213, v240, v241
	s_mov_b64 vcc, s[30:31]
	s_nop 0
	v_mov_b32_dpp v214, v212 quad_perm:[1,0,3,2] row_mask:0xf bank_mask:0xf
	v_mov_b32_dpp v215, v213 quad_perm:[1,0,3,2] row_mask:0xf bank_mask:0xf
	v_perm_b32 v216, v214, v212, v253
	v_perm_b32 v217, v215, v213, v253
	s_nop 1
	v_mov_b32_dpp v218, v216 quad_perm:[2,3,0,1] row_mask:0xf bank_mask:0xf
	v_mov_b32_dpp v219, v217 quad_perm:[2,3,0,1] row_mask:0xf bank_mask:0xf
	v_cndmask_b32_e32 v176, v216, v219, vcc
	v_cndmask_b32_e32 v177, v218, v217, vcc
	s_waitcnt lgkmcnt(0)
	s_mov_b64 vcc, s[28:29]
	v_cndmask_b32_e32 v208, v70, v78, vcc
	v_cndmask_b32_e32 v209, v71, v79, vcc
	v_cndmask_b32_e32 v210, v66, v74, vcc
	v_cndmask_b32_e32 v211, v67, v75, vcc
	ds_bpermute_b32 v200, v252, v208
	ds_bpermute_b32 v201, v252, v209
	ds_bpermute_b32 v202, v252, v210
	ds_bpermute_b32 v203, v252, v211
	v_pk_fma_f32 v[230:231], v[12:13], v[124:125], v[128:129] op_sel_hi:[1,0,0]
	v_pk_fma_f32 v[232:233], v[14:15], v[124:125], v[128:129] op_sel_hi:[1,0,0]
	v_fmac_f32_e32 v230, v205, v125
	v_fmac_f32_e32 v231, v12, v125
	v_fmac_f32_e32 v232, v13, v125
	v_fmac_f32_e32 v233, v14, v125
	v_pk_fma_f32 v[230:231], v[204:205], v[126:127], v[230:231] op_sel_hi:[1,0,1]
	v_pk_fma_f32 v[232:233], v[12:13], v[126:127], v[232:233] op_sel_hi:[1,0,1]
	v_pk_fma_f32 v[234:235], v[8:9], v[130:131], v[134:135] op_sel_hi:[1,0,0]
	v_pk_fma_f32 v[236:237], v[10:11], v[130:131], v[134:135] op_sel_hi:[1,0,0]
	v_fmac_f32_e32 v234, v207, v131
	v_fmac_f32_e32 v235, v8, v131
	v_fmac_f32_e32 v236, v9, v131
	v_fmac_f32_e32 v237, v10, v131
	v_pk_fma_f32 v[234:235], v[206:207], v[132:133], v[234:235] op_sel_hi:[1,0,1]
	v_pk_fma_f32 v[236:237], v[8:9], v[132:133], v[236:237] op_sel_hi:[1,0,1]
	v_pk_mul_f32 v[238:239], v[230:231], v[230:231]
	v_pk_mul_f32 v[240:241], v[232:233], v[232:233]
	v_pk_fma_f32 v[238:239], v[238:239], v[248:249], v[246:247]
	v_pk_fma_f32 v[240:241], v[240:241], v[248:249], v[246:247]
	v_pk_mul_f32 v[238:239], v[230:231], v[238:239]
	v_pk_mul_f32 v[240:241], v[232:233], v[240:241]
	v_exp_f32_e32 v238, v238
	v_exp_f32_e32 v239, v239
	v_exp_f32_e32 v240, v240
	v_exp_f32_e32 v241, v241
	v_pk_add_f32 v[238:239], v[238:239], 1.0 op_sel_hi:[1,0]
	v_pk_add_f32 v[240:241], v[240:241], 1.0 op_sel_hi:[1,0]
	v_rcp_f32_e32 v238, v238
	v_rcp_f32_e32 v239, v239
	v_rcp_f32_e32 v240, v240
	v_rcp_f32_e32 v241, v241
	v_pk_mul_f32 v[230:231], v[230:231], v[234:235]
	v_pk_mul_f32 v[232:233], v[232:233], v[236:237]
	v_pk_mul_f32 v[238:239], v[230:231], v[238:239]
	v_pk_mul_f32 v[240:241], v[232:233], v[240:241]
	v_cvt_pk_bf16_f32 v212, v238, v239
	v_cvt_pk_bf16_f32 v213, v240, v241
	s_mov_b64 vcc, s[30:31]
	s_nop 0
	v_mov_b32_dpp v214, v212 quad_perm:[1,0,3,2] row_mask:0xf bank_mask:0xf
	v_mov_b32_dpp v215, v213 quad_perm:[1,0,3,2] row_mask:0xf bank_mask:0xf
	v_perm_b32 v216, v214, v212, v253
	v_perm_b32 v217, v215, v213, v253
	s_nop 1
	v_mov_b32_dpp v218, v216 quad_perm:[2,3,0,1] row_mask:0xf bank_mask:0xf
	v_mov_b32_dpp v219, v217 quad_perm:[2,3,0,1] row_mask:0xf bank_mask:0xf
	v_cndmask_b32_e32 v178, v216, v219, vcc
	v_cndmask_b32_e32 v179, v218, v217, vcc
	s_movk_i32 s15, 0xf66
	v_cmp_gt_i32_e64 s[24:25], s15, v251
	s_add_u32 s84, s58, 0xd3c00
	s_addc_u32 s85, s59, 0
	s_mov_b64 exec, s[24:25]
	global_store_dwordx4 v250, v[176:179], s[84:85] nt
	s_mov_b64 exec, -1
	s_nop 0
	s_waitcnt lgkmcnt(0)
	s_mov_b64 vcc, s[28:29]
	v_cndmask_b32_e32 v208, v6, v14, vcc
	v_cndmask_b32_e32 v209, v7, v15, vcc
	v_cndmask_b32_e32 v210, v2, v10, vcc
	v_cndmask_b32_e32 v211, v3, v11, vcc
	ds_bpermute_b32 v204, v252, v208
	ds_bpermute_b32 v205, v252, v209
	ds_bpermute_b32 v206, v252, v210
	ds_bpermute_b32 v207, v252, v211
	v_pk_fma_f32 v[230:231], v[68:69], v[112:113], v[116:117] op_sel_hi:[1,0,0]
	v_pk_fma_f32 v[232:233], v[70:71], v[112:113], v[116:117] op_sel_hi:[1,0,0]
	v_fmac_f32_e32 v230, v201, v113
	v_fmac_f32_e32 v231, v68, v113
	v_fmac_f32_e32 v232, v69, v113
	v_fmac_f32_e32 v233, v70, v113
	v_pk_fma_f32 v[230:231], v[200:201], v[114:115], v[230:231] op_sel_hi:[1,0,1]
	v_pk_fma_f32 v[232:233], v[68:69], v[114:115], v[232:233] op_sel_hi:[1,0,1]
	v_pk_fma_f32 v[234:235], v[64:65], v[118:119], v[122:123] op_sel_hi:[1,0,0]
	v_pk_fma_f32 v[236:237], v[66:67], v[118:119], v[122:123] op_sel_hi:[1,0,0]
	v_fmac_f32_e32 v234, v203, v119
	v_fmac_f32_e32 v235, v64, v119
	v_fmac_f32_e32 v236, v65, v119
	v_fmac_f32_e32 v237, v66, v119
	v_pk_fma_f32 v[234:235], v[202:203], v[120:121], v[234:235] op_sel_hi:[1,0,1]
	v_pk_fma_f32 v[236:237], v[64:65], v[120:121], v[236:237] op_sel_hi:[1,0,1]
	v_pk_mul_f32 v[238:239], v[230:231], v[230:231]
	v_pk_mul_f32 v[240:241], v[232:233], v[232:233]
	v_pk_fma_f32 v[238:239], v[238:239], v[248:249], v[246:247]
	v_pk_fma_f32 v[240:241], v[240:241], v[248:249], v[246:247]
	v_pk_mul_f32 v[238:239], v[230:231], v[238:239]
	v_pk_mul_f32 v[240:241], v[232:233], v[240:241]
	v_exp_f32_e32 v238, v238
	v_exp_f32_e32 v239, v239
	v_exp_f32_e32 v240, v240
	v_exp_f32_e32 v241, v241
	v_pk_add_f32 v[238:239], v[238:239], 1.0 op_sel_hi:[1,0]
	v_pk_add_f32 v[240:241], v[240:241], 1.0 op_sel_hi:[1,0]
	v_rcp_f32_e32 v238, v238
	v_rcp_f32_e32 v239, v239
	v_rcp_f32_e32 v240, v240
	v_rcp_f32_e32 v241, v241
	v_pk_mul_f32 v[230:231], v[230:231], v[234:235]
	v_pk_mul_f32 v[232:233], v[232:233], v[236:237]
	v_pk_mul_f32 v[238:239], v[230:231], v[238:239]
	v_pk_mul_f32 v[240:241], v[232:233], v[240:241]
	v_cvt_pk_bf16_f32 v212, v238, v239
	v_cvt_pk_bf16_f32 v213, v240, v241
	s_mov_b64 vcc, s[30:31]
	s_nop 0
	v_mov_b32_dpp v214, v212 quad_perm:[1,0,3,2] row_mask:0xf bank_mask:0xf
	v_mov_b32_dpp v215, v213 quad_perm:[1,0,3,2] row_mask:0xf bank_mask:0xf
	v_perm_b32 v216, v214, v212, v253
	v_perm_b32 v217, v215, v213, v253
	s_nop 1
	v_mov_b32_dpp v218, v216 quad_perm:[2,3,0,1] row_mask:0xf bank_mask:0xf
	v_mov_b32_dpp v219, v217 quad_perm:[2,3,0,1] row_mask:0xf bank_mask:0xf
	v_cndmask_b32_e32 v180, v216, v219, vcc
	v_cndmask_b32_e32 v181, v218, v217, vcc
	s_waitcnt lgkmcnt(0)
	v_pk_fma_f32 v[230:231], v[4:5], v[124:125], v[128:129] op_sel_hi:[1,0,0]
	v_pk_fma_f32 v[232:233], v[6:7], v[124:125], v[128:129] op_sel_hi:[1,0,0]
	v_fmac_f32_e32 v230, v205, v125
	v_fmac_f32_e32 v231, v4, v125
	v_fmac_f32_e32 v232, v5, v125
	v_fmac_f32_e32 v233, v6, v125
	v_pk_fma_f32 v[230:231], v[204:205], v[126:127], v[230:231] op_sel_hi:[1,0,1]
	v_pk_fma_f32 v[232:233], v[4:5], v[126:127], v[232:233] op_sel_hi:[1,0,1]
	v_pk_fma_f32 v[234:235], v[0:1], v[130:131], v[134:135] op_sel_hi:[1,0,0]
	v_pk_fma_f32 v[236:237], v[2:3], v[130:131], v[134:135] op_sel_hi:[1,0,0]
	v_fmac_f32_e32 v234, v207, v131
	v_fmac_f32_e32 v235, v0, v131
	v_fmac_f32_e32 v236, v1, v131
	v_fmac_f32_e32 v237, v2, v131
	v_pk_fma_f32 v[234:235], v[206:207], v[132:133], v[234:235] op_sel_hi:[1,0,1]
	v_pk_fma_f32 v[236:237], v[0:1], v[132:133], v[236:237] op_sel_hi:[1,0,1]
	v_pk_mul_f32 v[238:239], v[230:231], v[230:231]
	v_pk_mul_f32 v[240:241], v[232:233], v[232:233]
	v_pk_fma_f32 v[238:239], v[238:239], v[248:249], v[246:247]
	v_pk_fma_f32 v[240:241], v[240:241], v[248:249], v[246:247]
	v_pk_mul_f32 v[238:239], v[230:231], v[238:239]
	v_pk_mul_f32 v[240:241], v[232:233], v[240:241]
	v_exp_f32_e32 v238, v238
	v_exp_f32_e32 v239, v239
	v_exp_f32_e32 v240, v240
	v_exp_f32_e32 v241, v241
	v_pk_add_f32 v[238:239], v[238:239], 1.0 op_sel_hi:[1,0]
	v_pk_add_f32 v[240:241], v[240:241], 1.0 op_sel_hi:[1,0]
	v_rcp_f32_e32 v238, v238
	v_rcp_f32_e32 v239, v239
	v_rcp_f32_e32 v240, v240
	v_rcp_f32_e32 v241, v241
	v_pk_mul_f32 v[230:231], v[230:231], v[234:235]
	v_pk_mul_f32 v[232:233], v[232:233], v[236:237]
	v_pk_mul_f32 v[238:239], v[230:231], v[238:239]
	v_pk_mul_f32 v[240:241], v[232:233], v[240:241]
	v_cvt_pk_bf16_f32 v212, v238, v239
	v_cvt_pk_bf16_f32 v213, v240, v241
	s_mov_b64 vcc, s[30:31]
	s_nop 0
	v_mov_b32_dpp v214, v212 quad_perm:[1,0,3,2] row_mask:0xf bank_mask:0xf
	v_mov_b32_dpp v215, v213 quad_perm:[1,0,3,2] row_mask:0xf bank_mask:0xf
	v_perm_b32 v216, v214, v212, v253
	v_perm_b32 v217, v215, v213, v253
	s_nop 1
	v_mov_b32_dpp v218, v216 quad_perm:[2,3,0,1] row_mask:0xf bank_mask:0xf
	v_mov_b32_dpp v219, v217 quad_perm:[2,3,0,1] row_mask:0xf bank_mask:0xf
	v_cndmask_b32_e32 v182, v216, v219, vcc
	v_cndmask_b32_e32 v183, v218, v217, vcc
	s_movk_i32 s15, 0xf56
	v_cmp_gt_i32_e64 s[24:25], s15, v251
	s_add_u32 s84, s58, 0xe9c00
	s_addc_u32 s85, s59, 0
	s_mov_b64 exec, s[24:25]
	global_store_dwordx4 v250, v[180:183], s[84:85] nt
	s_mov_b64 exec, -1
	s_nop 0
	s_mov_b64 s[0:1], -1
	s_branch .LBB0_619
	s_nop 0
	s_nop 0
	s_nop 0
	s_nop 0
	s_nop 0
	s_nop 0
	s_nop 0
	s_nop 0
	s_nop 0
	s_nop 0
	s_nop 0
	s_nop 0
	s_nop 0
	s_nop 0
	s_nop 0
	s_nop 0
	s_nop 0
	s_nop 0
	s_nop 0
	s_nop 0
	s_nop 0
	s_nop 0
	s_nop 0
	s_nop 0
	s_nop 0
	s_nop 0
	s_nop 0
	s_nop 0
	s_nop 0
	s_nop 0
	s_nop 0
	s_nop 0
	s_nop 0
	s_nop 0
	s_nop 0
	s_nop 0
	s_nop 0
	s_nop 0
	s_nop 0
	s_nop 0
	s_nop 0
	s_nop 0
	s_nop 0
	s_nop 0
	s_nop 0
	s_nop 0
	s_nop 0
	s_nop 0
	s_nop 0
	s_nop 0
	s_nop 0
	s_nop 0
	s_nop 0
	s_nop 0
	s_nop 0
	s_nop 0
	s_nop 0
	s_nop 0
	s_nop 0
	s_nop 0
	s_nop 0
	s_nop 0
	s_nop 0
	s_nop 0
	s_nop 0
	s_nop 0
	s_nop 0
	s_nop 0
	s_nop 0
	s_nop 0
	s_nop 0
	s_nop 0
	s_nop 0
	s_nop 0
	s_nop 0
	s_nop 0
	s_nop 0
	s_nop 0
	s_nop 0
	s_nop 0
	s_nop 0
	s_nop 0
	s_nop 0
	s_nop 0
	s_nop 0
	s_nop 0
	s_nop 0
	s_nop 0
	s_nop 0
	s_nop 0
	s_nop 0
	s_nop 0
	s_nop 0
	s_nop 0
	s_nop 0
	s_nop 0
	s_nop 0
	s_nop 0
	s_nop 0
	s_nop 0
	s_nop 0
	s_nop 0
	s_nop 0
	s_nop 0
	s_nop 0
	s_nop 0
	s_nop 0
	s_nop 0
	s_nop 0
	s_nop 0
	s_nop 0
	s_nop 0
	s_nop 0
	s_nop 0
	s_nop 0
	s_nop 0
	s_nop 0
	s_nop 0
	s_nop 0
	s_nop 0
	s_nop 0
	s_nop 0
	s_nop 0
	s_nop 0
	s_nop 0
	s_nop 0
	s_nop 0
	s_nop 0
	s_nop 0
	s_nop 0
	s_nop 0
	s_nop 0
	s_nop 0
	s_nop 0
	s_nop 0
	s_nop 0
	s_nop 0
	s_nop 0
	s_nop 0
	s_nop 0
	s_nop 0
	s_nop 0
	s_nop 0
	s_nop 0
	s_nop 0
	s_nop 0
	s_nop 0
	s_nop 0
	s_nop 0
	s_nop 0
	s_nop 0
	s_nop 0
	s_nop 0
	s_nop 0
	s_nop 0
	s_nop 0
	s_nop 0
	s_nop 0
	s_nop 0
	s_nop 0
	s_nop 0
	s_nop 0
	s_nop 0
	s_nop 0
	s_nop 0
	s_nop 0
	s_nop 0
	s_nop 0
	s_nop 0
	s_nop 0
	s_nop 0
	s_nop 0
	s_nop 0
	s_nop 0
	s_nop 0
	s_nop 0
	s_nop 0
	s_nop 0
	s_nop 0
	s_nop 0
	s_nop 0
	s_nop 0
	s_nop 0
	s_nop 0
	s_nop 0
	s_nop 0
	s_nop 0
	s_nop 0
	s_nop 0
	s_nop 0
	s_nop 0
	s_nop 0
	s_nop 0
	s_nop 0
	s_nop 0
	s_nop 0
	s_nop 0
	s_nop 0
	s_nop 0
	s_nop 0
	s_nop 0
	s_nop 0
	s_nop 0
	s_nop 0
	s_nop 0
	s_nop 0
	s_nop 0
	s_nop 0
	s_nop 0
	s_nop 0
	s_nop 0
	s_nop 0
	s_nop 0
	s_nop 0
	s_nop 0
	s_nop 0
	s_nop 0
	s_nop 0
	s_nop 0
	s_nop 0
	s_nop 0
	s_nop 0
	s_nop 0
	s_nop 0
	s_nop 0
	s_nop 0
	s_nop 0
	s_nop 0
	s_nop 0
	s_nop 0
	s_nop 0
	s_nop 0
	s_nop 0
	s_nop 0
